# GDN prep: dropped always-true range selects of conv window rows 2..17; next-unit window addresses by 64-bit adds instead of 20 clamp+mad
# baseline (speedup 1.0000x reference)
; __device__ __forceinline__ float siluf_(float x) { return x * frcp(1.f + fexp(-x)); }
;     ...
;     if (t < 384) {
;         const int pair = t % 96, rg = t / 96, c0 = 2 * pair, part = c0 >> 6, d0 = c0 & 63, zcol = part * 256 + h * 64 + d0;
;         float cw[5][2];
; #pragma unroll
;         for (int j = 0; j < 5; ++j) { const float* wp = F.conv_w + (size_t)(l * 5 + j) * 768 + part * 256 + h * 64 + d0; cw[j][0] = wp[0]; cw[j][1] = wp[1]; }
;         float win[20][2];
;         { const int rbase = row0 + rg * 16 - 2;
; #pragma unroll
;           for (int rr = 0; rr < 20; ++rr) { const int row = rbase + rr; const unsigned wv = (row >= seg_lo && row < seg_hi) ? P.raw[rr] : 0u; win[rr][0] = bflo(wv); win[rr][1] = bfhi(wv); } }
; #pragma unroll
;         for (int i = 0; i < 16; ++i) { float a0 = 0.f, a1 = 0.f;
; #pragma unroll
;             for (int j = 0; j < 5; ++j) { a0 += cw[j][0] * win[i + j][0]; a1 += cw[j][1] * win[i + j][1]; }
;             CV[(rg * 16 + i) * 196 + c0] = siluf_(a0); CV[(rg * 16 + i) * 196 + c0 + 1] = siluf_(a1); }
.LBB0_634:
	s_or_saveexec_b64 s[10:11], s[10:11]
	s_mov_b32 s5, 0x2aaaaaab
	v_mul_hi_i32 v0, v57, s5
	v_lshrrev_b32_e32 v65, 31, v0
	v_ashrrev_i32_e32 v69, 4, v0
	s_xor_b64 exec, exec, s[10:11]
	s_cbranch_execz .LBB0_636
	v_add_u32_e32 v60, v69, v65
	s_movk_i32 s5, 0x60
	v_mul_lo_u32 v0, v60, s5
	v_sub_u32_e32 v0, v57, v0
	v_lshlrev_b32_e32 v62, 3, v0
	v_and_b32_e32 v2, 0xffffff00, v62
	v_ashrrev_i32_e32 v3, 31, v2
	v_lshl_add_u64 v[2:3], v[2:3], 2, s[56:57]
	s_lshl_b32 s92, s4, 8
	v_lshl_add_u64 v[2:3], v[2:3], 0, s[92:93]
	v_and_b32_e32 v0, 0xf8, v62
	v_lshl_add_u64 v[2:3], v[2:3], 0, v[0:1]
	v_lshl_add_u64 v[28:29], v[2:3], 0, s[62:63]
	v_lshl_add_u64 v[30:31], v[2:3], 0, s[20:21]
	v_lshl_add_u64 v[32:33], v[2:3], 0, s[22:23]
	v_lshl_add_u64 v[34:35], v[2:3], 0, s[24:25]
	v_lshl_add_u64 v[36:37], v[2:3], 0, s[26:27]
	global_load_dwordx2 v[28:29], v[28:29], off
	s_nop 0
	global_load_dwordx2 v[30:31], v[30:31], off
	s_nop 0
	global_load_dwordx2 v[32:33], v[32:33], off
	s_nop 0
	global_load_dwordx2 v[34:35], v[34:35], off
	s_nop 0
	global_load_dwordx2 v[36:37], v[36:37], off
	v_lshlrev_b32_e32 v0, 4, v60
	s_add_i32 s3, s3, s0
	v_add3_u32 v10, s1, -2, v0
	v_cmp_le_i32_e32 vcc, s0, v10
	v_cmp_gt_i32_e64 s[40:41], s3, v10
	s_and_b64 vcc, vcc, s[40:41]
	s_waitcnt vmcnt(24)
	v_cndmask_b32_e32 v2, 0, v8, vcc
	v_lshlrev_b32_e32 v50, 16, v2
	v_and_b32_e32 v51, 0xffff0000, v2
	v_add_u32_e32 v2, 1, v10
	v_cmp_le_i32_e32 vcc, s0, v2
	v_cmp_gt_i32_e64 s[40:41], s3, v2
	s_and_b64 vcc, vcc, s[40:41]
	s_waitcnt vmcnt(23)
	v_cndmask_b32_e32 v2, 0, v9, vcc
	s_waitcnt vmcnt(22)
	v_lshlrev_b32_e32 v46, 16, v14
	v_and_b32_e32 v47, 0xffff0000, v14
	s_waitcnt vmcnt(21)
	v_lshlrev_b32_e32 v44, 16, v15
	v_and_b32_e32 v45, 0xffff0000, v15
	s_waitcnt vmcnt(20)
	v_lshlrev_b32_e32 v42, 16, v24
	v_and_b32_e32 v43, 0xffff0000, v24
	s_waitcnt vmcnt(19)
	v_lshlrev_b32_e32 v40, 16, v25
	v_and_b32_e32 v41, 0xffff0000, v25
	s_waitcnt vmcnt(18)
	v_lshlrev_b32_e32 v38, 16, v26
	v_and_b32_e32 v39, 0xffff0000, v26
	s_waitcnt vmcnt(17)
	v_lshlrev_b32_e32 v26, 16, v27
	v_and_b32_e32 v27, 0xffff0000, v27
	s_waitcnt vmcnt(16)
	v_lshlrev_b32_e32 v24, 16, v55
	v_and_b32_e32 v25, 0xffff0000, v55
	s_waitcnt vmcnt(15)
	v_lshlrev_b32_e32 v22, 16, v56
	v_and_b32_e32 v23, 0xffff0000, v56
	s_waitcnt vmcnt(14)
	v_lshlrev_b32_e32 v20, 16, v58
	v_and_b32_e32 v21, 0xffff0000, v58
	s_waitcnt vmcnt(13)
	v_lshlrev_b32_e32 v18, 16, v59
	v_and_b32_e32 v19, 0xffff0000, v59
	v_lshlrev_b32_e32 v48, 16, v2
	v_and_b32_e32 v49, 0xffff0000, v2
	s_waitcnt vmcnt(4)
	v_pk_fma_f32 v[50:51], v[28:29], v[50:51], 0 op_sel_hi:[1,1,0]
	s_waitcnt vmcnt(3)
	v_pk_fma_f32 v[50:51], v[30:31], v[48:49], v[50:51]
	s_waitcnt vmcnt(2)
	v_pk_fma_f32 v[50:51], v[32:33], v[46:47], v[50:51]
	v_lshlrev_b32_e32 v16, 16, v134
	v_and_b32_e32 v17, 0xffff0000, v134
	s_waitcnt vmcnt(1)
	v_pk_fma_f32 v[50:51], v[34:35], v[44:45], v[50:51]
	s_waitcnt vmcnt(0)
	v_pk_fma_f32 v[50:51], v[36:37], v[42:43], v[50:51]
	v_mul_f32_e32 v55, 0xbfb8aa3b, v50
	v_exp_f32_e32 v55, v55
	v_lshlrev_b32_e32 v14, 16, v135
	v_and_b32_e32 v15, 0xffff0000, v135
	v_add_f32_e32 v55, 1.0, v55
	v_lshlrev_b32_e32 v12, 16, v136
	v_and_b32_e32 v13, 0xffff0000, v136
	v_rcp_f32_e32 v58, v55
	v_mul_f32_e32 v55, 0xbfb8aa3b, v51
	v_exp_f32_e32 v55, v55
	v_pk_fma_f32 v[48:49], v[28:29], v[48:49], 0 op_sel_hi:[1,1,0]
	v_pk_fma_f32 v[48:49], v[30:31], v[46:47], v[48:49]
	v_pk_fma_f32 v[48:49], v[32:33], v[44:45], v[48:49]
	v_lshlrev_b32_e32 v2, 16, v137
	v_and_b32_e32 v3, 0xffff0000, v137
	v_pk_fma_f32 v[48:49], v[34:35], v[42:43], v[48:49]
	v_add_f32_e32 v55, 1.0, v55
	v_pk_fma_f32 v[48:49], v[36:37], v[40:41], v[48:49]
	v_rcp_f32_e32 v59, v55
	v_mul_f32_e32 v55, 0xbfb8aa3b, v48
	v_exp_f32_e32 v55, v55
	v_lshlrev_b32_e32 v4, 16, v138
	v_and_b32_e32 v5, 0xffff0000, v138
	v_add_f32_e32 v55, 1.0, v55
	v_lshlrev_b32_e32 v6, 16, v139
	v_and_b32_e32 v7, 0xffff0000, v139
	v_add_u32_e32 v0, 18, v10
	v_pk_mul_f32 v[50:51], v[50:51], v[58:59]
	v_rcp_f32_e32 v58, v55
	v_mul_f32_e32 v55, 0xbfb8aa3b, v49
	v_cmp_le_i32_e32 vcc, s0, v0
	v_cmp_gt_i32_e64 s[40:41], s3, v0
	v_exp_f32_e32 v55, v55
	s_and_b64 vcc, vcc, s[40:41]
	v_cndmask_b32_e32 v0, 0, v140, vcc
	v_lshlrev_b32_e32 v8, 16, v0
	v_and_b32_e32 v9, 0xffff0000, v0
	v_add_u32_e32 v0, 19, v10
	v_cmp_le_i32_e32 vcc, s0, v0
	v_cmp_gt_i32_e64 s[40:41], s3, v0
	v_add_f32_e32 v55, 1.0, v55
	s_and_b64 vcc, vcc, s[40:41]
	v_rcp_f32_e32 v59, v55
	v_pk_fma_f32 v[46:47], v[28:29], v[46:47], 0 op_sel_hi:[1,1,0]
	v_cndmask_b32_e32 v0, 0, v141, vcc
	s_movk_i32 s0, 0x3100
	v_pk_fma_f32 v[46:47], v[30:31], v[44:45], v[46:47]
	v_lshlrev_b32_e32 v10, 16, v0
	v_and_b32_e32 v11, 0xffff0000, v0
	v_mul_lo_u32 v0, v60, s0
	v_pk_fma_f32 v[46:47], v[32:33], v[42:43], v[46:47]
	v_add3_u32 v0, 0, v62, v0
	v_pk_fma_f32 v[46:47], v[34:35], v[40:41], v[46:47]
	v_pk_mul_f32 v[48:49], v[48:49], v[58:59]
	v_add_u32_e32 v55, 0x9800, v0
	v_pk_fma_f32 v[46:47], v[36:37], v[38:39], v[46:47]
	ds_write2_b64 v55, v[50:51], v[48:49] offset1:98
	v_mul_f32_e32 v48, 0xbfb8aa3b, v46
	v_mul_f32_e32 v49, 0xbfb8aa3b, v47
	v_exp_f32_e32 v48, v48
	v_exp_f32_e32 v49, v49
	v_pk_fma_f32 v[44:45], v[28:29], v[44:45], 0 op_sel_hi:[1,1,0]
	v_add_f32_e32 v48, 1.0, v48
	v_add_f32_e32 v49, 1.0, v49
	v_rcp_f32_e32 v48, v48
	v_rcp_f32_e32 v49, v49
	v_pk_fma_f32 v[44:45], v[30:31], v[42:43], v[44:45]
	v_pk_fma_f32 v[42:43], v[28:29], v[42:43], 0 op_sel_hi:[1,1,0]
	v_pk_fma_f32 v[44:45], v[32:33], v[40:41], v[44:45]
	v_pk_mul_f32 v[46:47], v[46:47], v[48:49]
	v_pk_fma_f32 v[44:45], v[34:35], v[38:39], v[44:45]
	v_pk_fma_f32 v[42:43], v[30:31], v[40:41], v[42:43]
; __device__ __forceinline__ float siluf_(float x) { return x * frcp(1.f + fexp(-x)); }
;     ...
;         for (int i = 0; i < 16; ++i) { float a0 = 0.f, a1 = 0.f;
; #pragma unroll
;             for (int j = 0; j < 5; ++j) { a0 += cw[j][0] * win[i + j][0]; a1 += cw[j][1] * win[i + j][1]; }
;             CV[(rg * 16 + i) * 196 + c0] = siluf_(a0); CV[(rg * 16 + i) * 196 + c0 + 1] = siluf_(a1); }
	v_pk_fma_f32 v[44:45], v[36:37], v[26:27], v[44:45]
	v_pk_fma_f32 v[42:43], v[32:33], v[38:39], v[42:43]
	v_mul_f32_e32 v48, 0xbfb8aa3b, v44
	v_mul_f32_e32 v49, 0xbfb8aa3b, v45
	v_exp_f32_e32 v48, v48
	v_exp_f32_e32 v49, v49
	v_pk_fma_f32 v[42:43], v[34:35], v[26:27], v[42:43]
	v_pk_fma_f32 v[40:41], v[28:29], v[40:41], 0 op_sel_hi:[1,1,0]
	v_add_f32_e32 v48, 1.0, v48
	v_add_f32_e32 v49, 1.0, v49
	v_rcp_f32_e32 v48, v48
	v_rcp_f32_e32 v49, v49
	v_pk_fma_f32 v[42:43], v[36:37], v[24:25], v[42:43]
	v_pk_fma_f32 v[40:41], v[30:31], v[38:39], v[40:41]
	v_pk_fma_f32 v[38:39], v[28:29], v[38:39], 0 op_sel_hi:[1,1,0]
	v_pk_mul_f32 v[44:45], v[44:45], v[48:49]
	v_add_u32_e32 v48, 0x9c00, v0
	ds_write2_b64 v48, v[46:47], v[44:45] offset0:68 offset1:166
	v_mul_f32_e32 v44, 0xbfb8aa3b, v42
	v_mul_f32_e32 v45, 0xbfb8aa3b, v43
	v_exp_f32_e32 v44, v44
	v_exp_f32_e32 v45, v45
	v_pk_fma_f32 v[40:41], v[32:33], v[26:27], v[40:41]
	v_pk_fma_f32 v[38:39], v[30:31], v[26:27], v[38:39]
	v_add_f32_e32 v44, 1.0, v44
	v_add_f32_e32 v45, 1.0, v45
	v_rcp_f32_e32 v44, v44
	v_rcp_f32_e32 v45, v45
	v_pk_fma_f32 v[40:41], v[34:35], v[24:25], v[40:41]
	v_pk_fma_f32 v[38:39], v[32:33], v[24:25], v[38:39]
	v_pk_fma_f32 v[40:41], v[36:37], v[22:23], v[40:41]
	v_pk_mul_f32 v[42:43], v[42:43], v[44:45]
	v_mul_f32_e32 v44, 0xbfb8aa3b, v40
	v_mul_f32_e32 v45, 0xbfb8aa3b, v41
	v_exp_f32_e32 v44, v44
	v_exp_f32_e32 v45, v45
	v_pk_fma_f32 v[38:39], v[34:35], v[22:23], v[38:39]
	v_pk_fma_f32 v[26:27], v[28:29], v[26:27], 0 op_sel_hi:[1,1,0]
	v_add_f32_e32 v44, 1.0, v44
	v_add_f32_e32 v45, 1.0, v45
	v_rcp_f32_e32 v44, v44
	v_rcp_f32_e32 v45, v45
	v_pk_fma_f32 v[38:39], v[36:37], v[20:21], v[38:39]
	v_pk_fma_f32 v[26:27], v[30:31], v[24:25], v[26:27]
	v_pk_fma_f32 v[24:25], v[28:29], v[24:25], 0 op_sel_hi:[1,1,0]
	v_pk_mul_f32 v[40:41], v[40:41], v[44:45]
	v_add_u32_e32 v44, 0xa000, v0
	ds_write2_b64 v44, v[42:43], v[40:41] offset0:136 offset1:234
	v_mul_f32_e32 v40, 0xbfb8aa3b, v38
	v_mul_f32_e32 v41, 0xbfb8aa3b, v39
	v_exp_f32_e32 v40, v40
	v_exp_f32_e32 v41, v41
	v_pk_fma_f32 v[26:27], v[32:33], v[22:23], v[26:27]
	v_pk_fma_f32 v[24:25], v[30:31], v[22:23], v[24:25]
	v_add_f32_e32 v40, 1.0, v40
	v_add_f32_e32 v41, 1.0, v41
	v_rcp_f32_e32 v40, v40
	v_rcp_f32_e32 v41, v41
	v_pk_fma_f32 v[26:27], v[34:35], v[20:21], v[26:27]
	v_pk_fma_f32 v[24:25], v[32:33], v[20:21], v[24:25]
	v_pk_fma_f32 v[26:27], v[36:37], v[18:19], v[26:27]
	v_pk_mul_f32 v[38:39], v[38:39], v[40:41]
	v_mul_f32_e32 v40, 0xbfb8aa3b, v26
	v_mul_f32_e32 v41, 0xbfb8aa3b, v27
	v_exp_f32_e32 v40, v40
	v_exp_f32_e32 v41, v41
	v_pk_fma_f32 v[24:25], v[34:35], v[18:19], v[24:25]
	v_pk_fma_f32 v[22:23], v[28:29], v[22:23], 0 op_sel_hi:[1,1,0]
	v_add_f32_e32 v40, 1.0, v40
	v_add_f32_e32 v41, 1.0, v41
	v_rcp_f32_e32 v40, v40
	v_rcp_f32_e32 v41, v41
	v_pk_fma_f32 v[24:25], v[36:37], v[16:17], v[24:25]
	v_pk_fma_f32 v[22:23], v[30:31], v[20:21], v[22:23]
	v_pk_fma_f32 v[20:21], v[28:29], v[20:21], 0 op_sel_hi:[1,1,0]
	v_pk_mul_f32 v[26:27], v[26:27], v[40:41]
	v_add_u32_e32 v40, 0xa800, v0
	ds_write2_b64 v40, v[38:39], v[26:27] offset0:76 offset1:174
	v_mul_f32_e32 v26, 0xbfb8aa3b, v24
	v_mul_f32_e32 v27, 0xbfb8aa3b, v25
	v_exp_f32_e32 v26, v26
	v_exp_f32_e32 v27, v27
	v_pk_fma_f32 v[22:23], v[32:33], v[18:19], v[22:23]
	v_pk_fma_f32 v[20:21], v[30:31], v[18:19], v[20:21]
	v_add_f32_e32 v26, 1.0, v26
	v_add_f32_e32 v27, 1.0, v27
	v_rcp_f32_e32 v26, v26
	v_rcp_f32_e32 v27, v27
	v_pk_fma_f32 v[22:23], v[34:35], v[16:17], v[22:23]
	v_pk_fma_f32 v[20:21], v[32:33], v[16:17], v[20:21]
	v_pk_fma_f32 v[22:23], v[36:37], v[14:15], v[22:23]
	v_pk_mul_f32 v[24:25], v[24:25], v[26:27]
; __device__ __forceinline__ float siluf_(float x) { return x * frcp(1.f + fexp(-x)); }
;     ...
;         for (int i = 0; i < 16; ++i) { float a0 = 0.f, a1 = 0.f;
; #pragma unroll
;             for (int j = 0; j < 5; ++j) { a0 += cw[j][0] * win[i + j][0]; a1 += cw[j][1] * win[i + j][1]; }
;             CV[(rg * 16 + i) * 196 + c0] = siluf_(a0); CV[(rg * 16 + i) * 196 + c0 + 1] = siluf_(a1); }
	v_mul_f32_e32 v26, 0xbfb8aa3b, v22
	v_mul_f32_e32 v27, 0xbfb8aa3b, v23
	v_exp_f32_e32 v26, v26
	v_exp_f32_e32 v27, v27
	v_pk_fma_f32 v[20:21], v[34:35], v[14:15], v[20:21]
	v_pk_fma_f32 v[18:19], v[28:29], v[18:19], 0 op_sel_hi:[1,1,0]
	v_add_f32_e32 v26, 1.0, v26
	v_add_f32_e32 v27, 1.0, v27
	v_rcp_f32_e32 v26, v26
	v_rcp_f32_e32 v27, v27
	v_pk_fma_f32 v[20:21], v[36:37], v[12:13], v[20:21]
	v_pk_fma_f32 v[18:19], v[30:31], v[16:17], v[18:19]
	v_pk_fma_f32 v[16:17], v[28:29], v[16:17], 0 op_sel_hi:[1,1,0]
	v_pk_mul_f32 v[22:23], v[22:23], v[26:27]
	v_add_u32_e32 v26, 0xb000, v0
	ds_write2_b64 v26, v[24:25], v[22:23] offset0:16 offset1:114
	v_mul_f32_e32 v22, 0xbfb8aa3b, v20
	v_mul_f32_e32 v23, 0xbfb8aa3b, v21
	v_exp_f32_e32 v22, v22
	v_exp_f32_e32 v23, v23
	v_pk_fma_f32 v[18:19], v[32:33], v[14:15], v[18:19]
	v_pk_fma_f32 v[16:17], v[30:31], v[14:15], v[16:17]
	v_add_f32_e32 v22, 1.0, v22
	v_add_f32_e32 v23, 1.0, v23
	v_rcp_f32_e32 v22, v22
	v_rcp_f32_e32 v23, v23
	v_pk_fma_f32 v[18:19], v[34:35], v[12:13], v[18:19]
	v_pk_fma_f32 v[16:17], v[32:33], v[12:13], v[16:17]
	v_pk_fma_f32 v[18:19], v[36:37], v[2:3], v[18:19]
	v_pk_mul_f32 v[20:21], v[20:21], v[22:23]
	v_mul_f32_e32 v22, 0xbfb8aa3b, v18
	v_mul_f32_e32 v23, 0xbfb8aa3b, v19
	v_exp_f32_e32 v22, v22
	v_exp_f32_e32 v23, v23
	v_pk_fma_f32 v[16:17], v[34:35], v[2:3], v[16:17]
	v_pk_fma_f32 v[14:15], v[28:29], v[14:15], 0 op_sel_hi:[1,1,0]
	v_add_f32_e32 v22, 1.0, v22
	v_add_f32_e32 v23, 1.0, v23
	v_rcp_f32_e32 v22, v22
	v_rcp_f32_e32 v23, v23
	v_pk_fma_f32 v[16:17], v[36:37], v[4:5], v[16:17]
	v_pk_fma_f32 v[14:15], v[30:31], v[12:13], v[14:15]
	v_pk_fma_f32 v[12:13], v[28:29], v[12:13], 0 op_sel_hi:[1,1,0]
	v_pk_mul_f32 v[18:19], v[18:19], v[22:23]
	v_add_u32_e32 v22, 0xb400, v0
	ds_write2_b64 v22, v[20:21], v[18:19] offset0:84 offset1:182
	v_mul_f32_e32 v18, 0xbfb8aa3b, v16
	v_mul_f32_e32 v19, 0xbfb8aa3b, v17
	v_exp_f32_e32 v18, v18
	v_exp_f32_e32 v19, v19
	v_pk_fma_f32 v[14:15], v[32:33], v[2:3], v[14:15]
	v_pk_fma_f32 v[12:13], v[30:31], v[2:3], v[12:13]
	v_add_f32_e32 v18, 1.0, v18
	v_add_f32_e32 v19, 1.0, v19
	v_rcp_f32_e32 v18, v18
	v_rcp_f32_e32 v19, v19
	v_pk_fma_f32 v[14:15], v[34:35], v[4:5], v[14:15]
	v_pk_fma_f32 v[2:3], v[28:29], v[2:3], 0 op_sel_hi:[1,1,0]
	v_pk_fma_f32 v[14:15], v[36:37], v[6:7], v[14:15]
	v_pk_mul_f32 v[16:17], v[16:17], v[18:19]
	v_mul_f32_e32 v18, 0xbfb8aa3b, v14
	v_mul_f32_e32 v19, 0xbfb8aa3b, v15
	v_exp_f32_e32 v18, v18
	v_exp_f32_e32 v19, v19
	v_pk_fma_f32 v[2:3], v[30:31], v[4:5], v[2:3]
	v_pk_fma_f32 v[12:13], v[32:33], v[4:5], v[12:13]
	v_add_f32_e32 v18, 1.0, v18
	v_add_f32_e32 v19, 1.0, v19
	v_rcp_f32_e32 v18, v18
	v_rcp_f32_e32 v19, v19
	v_pk_fma_f32 v[2:3], v[32:33], v[6:7], v[2:3]
	v_pk_fma_f32 v[12:13], v[34:35], v[6:7], v[12:13]
	v_pk_fma_f32 v[2:3], v[34:35], v[8:9], v[2:3]
	v_pk_mul_f32 v[14:15], v[14:15], v[18:19]
	v_add_u32_e32 v18, 0xb800, v0
	v_pk_fma_f32 v[12:13], v[36:37], v[8:9], v[12:13]
	v_pk_fma_f32 v[2:3], v[36:37], v[10:11], v[2:3]
	ds_write2_b64 v18, v[16:17], v[14:15] offset0:152 offset1:250
	v_mul_f32_e32 v14, 0xbfb8aa3b, v12
	v_mul_f32_e32 v15, 0xbfb8aa3b, v13
	v_mul_f32_e32 v4, 0xbfb8aa3b, v2
	v_mul_f32_e32 v5, 0xbfb8aa3b, v3
	v_exp_f32_e32 v14, v14
	v_exp_f32_e32 v15, v15
	v_exp_f32_e32 v4, v4
	v_exp_f32_e32 v5, v5
	v_add_f32_e32 v14, 1.0, v14
	v_add_f32_e32 v15, 1.0, v15
	v_add_f32_e32 v4, 1.0, v4
	v_add_f32_e32 v5, 1.0, v5
	v_rcp_f32_e32 v14, v14
	v_rcp_f32_e32 v15, v15
	v_rcp_f32_e32 v4, v4
	v_rcp_f32_e32 v5, v5
	v_add_u32_e32 v0, 0xc000, v0
	v_pk_mul_f32 v[12:13], v[12:13], v[14:15]
	v_pk_mul_f32 v[2:3], v[2:3], v[4:5]
	ds_write2_b64 v0, v[12:13], v[2:3] offset0:92 offset1:190

; #define LAS __attribute__((address_space(3)))
; __device__ __forceinline__ void gdn_preload(const Frame& F, int u, int t, GdnPre& P) {
;     const int b = u / 144, h = (u / 36) & 3, cidx = u % 36, row0 = chunk_row0(b, cidx);
;     const int seg_lo = cidx < 4 ? MLAT + b * CTXL : b * SEQ, seg_hi = seg_lo + (cidx < 4 ? CTXL : SEQ);
;     if (t < 384) {
;         const int pair = t % 96, rg = t / 96, c0 = 2 * pair, part = c0 >> 6, d0 = c0 & 63, zcol = part * 256 + h * 64 + d0;
;         const int rbase = row0 + rg * 16 - 2; const bf16_t* zc = F.Z + zcol;
; #pragma unroll
;         for (int rr = 0; rr < 20; ++rr) { int row = rbase + rr; row = row < seg_lo ? seg_lo : (row >= seg_hi ? seg_hi - 1 : row); P.raw[rr] = *(const unsigned*)(zc + (size_t)row * ZW); }
;     ...
;     for (int d = 0; d < 2; ++d) {
;         const int ud = u * 2 + d; const float tot = totS[d];
;         const LAS bf16_t* T0 = Tb + d * 9216; const LAS bf16_t* T1 = T0 + 4608; const LAS bf16_t* Ad = At + d * 4608;
;         {
;             const bool isw = w >= 4; const LAS bf16_t* Aop = isw ? T1 : T0; const LAS bf16_t* Bop = isw ? Kt : Vt;
;             LAS bf16_t* o0 = isw ? WT : UT; LAS bf16_t* o1 = isw ? WTd : UTd;
; #pragma unroll
.LBB0_644:
	s_cmp_gt_i32 s28, 3
	s_cselect_b32 s6, s76, s77
	s_add_i32 s1, 0, 0xe000
	s_cmp_gt_i32 s28, 3
	s_cselect_b32 s7, s1, s2
	s_add_i32 s3, 0, 0x4800
	s_cmp_gt_i32 s28, 3
	v_readlane_b32 s4, v253, 56
	s_cselect_b32 s8, 0x2400, 0
	s_cselect_b32 s12, s3, s4
	s_add_i32 s4, s34, 0x100
	s_cmpk_gt_i32 s34, 0x37f
	s_cselect_b64 s[10:11], -1, 0
	s_cmpk_lt_i32 s34, 0x380
	s_cselect_b32 s13, s4, -1
	s_lshl_b32 s14, s28, 4
	s_and_b32 s14, s14, 48
	s_add_i32 s8, s8, 0
	s_mul_i32 s15, s14, 0x90
	s_add_i32 s8, s8, s15
	s_add_i32 s8, s8, 0x12800
	v_or_b32_e32 v0, s14, v17
	v_add3_u32 v63, s8, v113, v117
	v_lshl_add_u32 v110, v0, 2, 0
	v_lshlrev_b32_e32 v0, 1, v0
	s_ashr_i32 s8, s28, 1
	v_add_u32_e32 v4, s7, v0
	v_add_u32_e32 v0, s6, v0
	s_lshl_b32 s6, s8, 12
	s_ashr_i32 s7, s6, 31
	s_lshl_b32 s5, s34, 1
	v_add3_u32 v108, s12, v113, v117
	s_lshl_b64 s[6:7], s[6:7], 1
	v_readlane_b32 s12, v254, 59
	s_add_u32 s6, s12, s6
	v_readlane_b32 s12, v254, 60
	s_addc_u32 s7, s12, s7
	s_cmp_lt_u32 s28, 2
	s_cselect_b64 s[40:41], -1, 0
	s_cmp_eq_u32 s8, 1
	s_cselect_b64 s[28:29], -1, 0
	s_cmp_eq_u32 s8, 2
	s_cselect_b64 s[30:31], -1, 0
	s_and_b32 s12, s0, 8
	s_cmp_lt_i32 s13, 0
	s_cselect_b32 s0, s34, s13
	s_mul_hi_i32 s8, s0, 0x38e38e39
	s_ashr_i32 s13, s8, 5
	s_lshr_b32 s14, s8, 31
	s_ashr_i32 s8, s8, 3
	s_add_i32 s8, s8, s14
	s_add_i32 s13, s13, s14
	s_and_b32 s14, s8, 3
	s_mul_i32 s8, s8, 36
	s_or_b32 s49, s12, 6
	s_sub_i32 s0, s0, s8
	s_lshl_b32 s15, s13, 11
	s_lshl_b32 s8, s13, 8
	s_or_b64 s[34:35], s[40:41], s[30:31]
	s_lshl_b32 s42, s49, 2
	s_lshl_b32 s33, s0, 6
	s_add_i32 s44, s15, 0xffffff00
	s_add_i32 s13, s8, 0x4000
	s_lshl_b32 s8, s14, 6
	s_xor_b64 s[36:37], s[34:35], -1
	s_lshl_b32 s45, s12, 3
	s_or_b32 s48, s12, 4
	s_and_b32 s50, s42, 48
	v_mul_u32_u24_e32 v9, 0x48, v109
	s_cmp_lt_i32 s0, 4
	v_and_b32_e32 v2, 0xffffffc, v61
	v_lshlrev_b32_e32 v9, 1, v9
	v_or_b32_e32 v2, s14, v2
	v_add_u32_e32 v11, 0x900, v9
	s_cselect_b32 s14, s13, s15
	s_cselect_b32 s13, s13, s44
	s_movk_i32 s15, 0x7ff
	v_add_u32_e32 v6, v69, v65
	v_add_u32_e32 v61, v4, v9
	v_add_u32_e32 v111, v0, v9
	v_add_u32_e32 v112, v4, v11
	v_add_u32_e32 v114, v0, v11
	v_add_u32_e32 v11, 0x1200, v9
	v_add_u32_e32 v9, 0x1b00, v9
	s_cselect_b32 s15, 0xff, s15
	s_add_i32 s13, s13, s33
	s_movk_i32 s0, 0x60
	v_add_u32_e32 v115, v4, v11
	v_add_u32_e32 v118, v4, v9
	v_lshl_add_u32 v4, v6, 4, s13
	v_lshlrev_b32_e32 v5, 1, v2
	v_mul_lo_u32 v2, v6, s0
	v_or_b32_e32 v10, 16, v109
	v_add_u32_e32 v15, -2, v4
	s_add_i32 s15, s15, s14
	v_mad_u32_u24 v122, v10, s92, 0
	v_and_b32_e32 v8, 4, v17
	v_sub_u32_e32 v2, v57, v2
	v_lshlrev_b32_e32 v3, 1, v2
	v_lshlrev_b32_e32 v2, 3, v2
	v_add_u32_e32 v116, v0, v11
	v_add_u32_e32 v119, v0, v9
	v_or_b32_e32 v0, s12, v13
	v_and_b32_e32 v3, 62, v3
	v_and_b32_e32 v2, 0xffffff00, v2
	s_mul_i32 s0, s12, 0x240
	v_lshlrev_b32_e32 v120, 3, v0
	v_or_b32_e32 v0, s48, v13
	v_or3_b32 v2, v2, s8, v3
	v_lshlrev_b32_e32 v13, 3, v0
	v_or_b32_e32 v0, s13, v53
	v_mov_b64_e32 v[18:19], s[16:17]
	v_ashrrev_i32_e32 v3, 31, v2
	v_add_u32_e32 v9, 0x900, v122
	v_add_u32_e32 v11, 0x1200, v122
	v_lshl_add_u64 v[2:3], v[2:3], 1, s[16:17]
	s_mov_b32 s9, 0
	v_lshlrev_b32_e32 v12, 3, v53
	v_lshl_or_b32 v60, s12, 8, v12
	v_and_b32_e32 v6, 16, v7
	s_lshl_b32 s12, s49, 8
	v_or3_b32 v4, v6, s45, v109
	v_or3_b32 v6, v109, v6, s45
	s_and_b32 s12, s12, 0xc00
	v_lshl_or_b32 v4, v4, 3, v8
	v_lshl_or_b32 v62, v6, 3, v8
	v_lshl_or_b32 v6, s48, 8, v12
	v_or_b32_e32 v12, s12, v12
	v_mad_i64_i32 v[18:19], s[12:13], v0, s66, v[18:19]
	v_add_u32_e32 v0, 0x1800, v5
	v_or_b32_e32 v8, 0x100, v4
	v_or_b32_e32 v10, 0x500, v4
	v_or_b32_e32 v14, 0x900, v4
	v_or_b32_e32 v16, 0xd00, v4
	v_lshl_add_u64 v[64:65], v[18:19], 0, v[0:1]
	v_add_u32_e32 v0, 0x1810, v5
	s_mov_b64 s[46:47], -1
	v_cmp_eq_u32_e64 s[42:43], 0, v57
	s_mul_i32 s8, s50, 0x90
	v_lshl_add_u64 v[66:67], v[18:19], 0, v[0:1]
	v_mad_i64_i32 v[68:69], s[12:13], v15, s66, v[2:3]
	s_mov_b32 s98, s66
	s_mov_b32 s99, 0
	v_lshl_add_u64 v[70:71], v[68:69], 0, s[98:99]
	v_lshl_add_u64 v[72:73], v[70:71], 0, s[98:99]
	v_lshl_add_u64 v[74:75], v[72:73], 0, s[98:99]
	v_lshl_add_u64 v[76:77], v[74:75], 0, s[98:99]
	v_lshl_add_u64 v[78:79], v[76:77], 0, s[98:99]
	v_lshl_add_u64 v[80:81], v[78:79], 0, s[98:99]
	v_lshl_add_u64 v[82:83], v[80:81], 0, s[98:99]
	v_lshl_add_u64 v[84:85], v[82:83], 0, s[98:99]
	v_lshl_add_u64 v[86:87], v[84:85], 0, s[98:99]
	v_lshl_add_u64 v[88:89], v[86:87], 0, s[98:99]
	v_lshl_add_u64 v[90:91], v[88:89], 0, s[98:99]
	v_lshl_add_u64 v[92:93], v[90:91], 0, s[98:99]
	v_lshl_add_u64 v[94:95], v[92:93], 0, s[98:99]
	v_lshl_add_u64 v[96:97], v[94:95], 0, s[98:99]
	v_lshl_add_u64 v[98:99], v[96:97], 0, s[98:99]
	v_lshl_add_u64 v[100:101], v[98:99], 0, s[98:99]
	v_lshl_add_u64 v[102:103], v[100:101], 0, s[98:99]
	v_lshl_add_u64 v[104:105], v[102:103], 0, s[98:99]
	v_lshl_add_u64 v[106:107], v[104:105], 0, s[98:99]
	v_add_u32_e32 v123, v121, v13
	v_lshlrev_b32_e32 v124, 1, v4
	v_lshlrev_b32_e32 v125, 1, v6
	v_lshlrev_b32_e32 v126, 1, v8
	v_lshlrev_b32_e32 v127, 1, v12
	v_lshlrev_b32_e32 v128, 1, v10
	v_lshlrev_b32_e32 v129, 1, v14
	v_lshlrev_b32_e32 v130, 1, v16
	v_add_u32_e32 v131, v9, v120
	v_add_u32_e32 v132, v11, v120
	s_waitcnt lgkmcnt(0)
	s_barrier
	s_branch .LBB0_646
